# scan chunk D1 stage: 12 fragment reads issued up front with counted lgkmcnt waits (on top of rw-phase change)
# baseline (speedup 1.0000x reference)
; DI void scan_phase(unsigned char* sl, int layer, bool ctx_out, bool do_store, LAS unsigned char* lds) {
;     ...
;         __syncthreads();
; #pragma unroll
;         for (int t = 0; t < 2; ++t)
; #pragma unroll
;             for (int g = 0; g < 4; ++g) { const int k0 = 32 * (kb0 + t) + 8 * g + 4 * hh; const f32x4 ea = *(const LAS f32x4*)(vec + k0);
;                 u32x2 w; w.x = cvtpk(sacc[t][4 * g] * ea[0], sacc[t][4 * g + 1] * ea[1]); w.y = cvtpk(sacc[t][4 * g + 2] * ea[2], sacc[t][4 * g + 3] * ea[3]);
;                 *(LAS u32x2*)(lds + SC_ST + (32 * vb + r32) * 272 + k0 * 2) = w; }
;         __syncthreads();
;         f32x16 d1[2];
; #pragma unroll
;         for (int t = 0; t < 2; ++t) {
; #pragma unroll
;             for (int i = 0; i < 16; ++i) d1[t][i] = 0.f;
; #pragma unroll
;             for (int s = 0; s < 4; ++s) { const bf16x8 af = *(const LAS bf16x8*)(lds + SC_KT + (32 * (kb0 + t) + r32) * 144 + (16 * s + 8 * hh) * 2);
;                 const bf16x8 bfv = *(const LAS bf16x8*)(lds + SC_VT + (32 * vb + r32) * 144 + (16 * s + 8 * hh) * 2);
;                 d1[t] = MFMA32(af, bfv, d1[t]); }
;         }
;         if (need_out) {
;             f32x16 o, p0, p1;
; #pragma unroll
;             for (int i = 0; i < 16; ++i) { o[i] = 0.f; p0[i] = 0.f; p1[i] = 0.f; }
;             bf16x8 qf[8];
; #pragma unroll
;             for (int s = 0; s < 8; ++s) qf[s] = *(const LAS bf16x8*)(lds + SC_QH + (32 * tb + r32) * 272 + (16 * s + 8 * hh) * 2);
;             if (tb == 1) {
; #pragma unroll
;                 for (int s = 0; s < 8; ++s) { const bf16x8 sf = *(const LAS bf16x8*)(lds + SC_ST + (32 * vb + r32) * 272 + (16 * s + 8 * hh) * 2);
;                     const bf16x8 k0 = *(const LAS bf16x8*)(lds + SC_KH + r32 * 272 + (16 * s + 8 * hh) * 2), k1 = *(const LAS bf16x8*)(lds + SC_KH + (32 + r32) * 272 + (16 * s + 8 * hh) * 2);
;                     o = MFMA32(sf, qf[s], o); p0 = MFMA32(k0, qf[s], p0); p1 = MFMA32(k1, qf[s], p1); }
; #pragma unroll
;                 for (int i = 0; i < 16; ++i) if (crow(i, hh) > r32) p1[i] = 0.f;
;             } else {
; #pragma unroll
;                 for (int s = 0; s < 8; ++s) { const bf16x8 sf = *(const LAS bf16x8*)(lds + SC_ST + (32 * vb + r32) * 272 + (16 * s + 8 * hh) * 2);
;                     const bf16x8 k0 = *(const LAS bf16x8*)(lds + SC_KH + r32 * 272 + (16 * s + 8 * hh) * 2);
.LBB0_316:
	s_waitcnt lgkmcnt(0)
	s_barrier
	ds_read_b128 v[2:5], v193
	v_add_u32_e32 v42, v173, v172
	s_and_b64 s[64:65], s[8:9], s[64:65]
	s_and_b64 vcc, exec, s[64:65]
	s_waitcnt lgkmcnt(0)
	v_pk_mul_f32 v[2:3], v[120:121], v[2:3]
	v_pk_mul_f32 v[4:5], v[122:123], v[4:5]
	v_cvt_pk_bf16_f32 v2, v2, v3
	v_cvt_pk_bf16_f32 v3, v4, v5
	ds_write_b64 v232, v[2:3]
	ds_read_b128 v[2:5], v195
	s_waitcnt lgkmcnt(0)
	v_pk_mul_f32 v[2:3], v[124:125], v[2:3]
	v_pk_mul_f32 v[4:5], v[126:127], v[4:5]
	v_cvt_pk_bf16_f32 v2, v2, v3
	v_cvt_pk_bf16_f32 v3, v4, v5
	ds_write_b64 v233, v[2:3]
	ds_read_b128 v[2:5], v196
	s_waitcnt lgkmcnt(0)
	v_pk_mul_f32 v[2:3], v[128:129], v[2:3]
	v_pk_mul_f32 v[4:5], v[130:131], v[4:5]
	v_cvt_pk_bf16_f32 v2, v2, v3
	v_cvt_pk_bf16_f32 v3, v4, v5
	ds_write_b64 v234, v[2:3]
	ds_read_b128 v[2:5], v197
	s_waitcnt lgkmcnt(0)
	v_pk_mul_f32 v[2:3], v[132:133], v[2:3]
	v_pk_mul_f32 v[4:5], v[134:135], v[4:5]
	v_cvt_pk_bf16_f32 v2, v2, v3
	v_cvt_pk_bf16_f32 v3, v4, v5
	ds_write_b64 v235, v[2:3]
	ds_read_b128 v[2:5], v198
	s_waitcnt lgkmcnt(0)
	v_pk_mul_f32 v[2:3], v[136:137], v[2:3]
	v_pk_mul_f32 v[4:5], v[138:139], v[4:5]
	v_cvt_pk_bf16_f32 v2, v2, v3
	v_cvt_pk_bf16_f32 v3, v4, v5
	ds_write_b64 v237, v[2:3]
	ds_read_b128 v[2:5], v200
	s_waitcnt lgkmcnt(0)
	v_pk_mul_f32 v[2:3], v[140:141], v[2:3]
	v_pk_mul_f32 v[4:5], v[142:143], v[4:5]
	v_cvt_pk_bf16_f32 v2, v2, v3
	v_cvt_pk_bf16_f32 v3, v4, v5
	ds_write_b64 v238, v[2:3]
	ds_read_b128 v[2:5], v202
	s_waitcnt lgkmcnt(0)
	v_pk_mul_f32 v[2:3], v[144:145], v[2:3]
	v_pk_mul_f32 v[4:5], v[146:147], v[4:5]
	v_cvt_pk_bf16_f32 v2, v2, v3
	v_cvt_pk_bf16_f32 v3, v4, v5
	ds_write_b64 v239, v[2:3]
	ds_read_b128 v[2:5], v203
	s_waitcnt lgkmcnt(0)
	v_pk_mul_f32 v[2:3], v[148:149], v[2:3]
	v_pk_mul_f32 v[4:5], v[150:151], v[4:5]
	v_cvt_pk_bf16_f32 v2, v2, v3
	v_cvt_pk_bf16_f32 v3, v4, v5
	ds_write_b64 v240, v[2:3]
	s_waitcnt lgkmcnt(0)
	s_barrier
	ds_read_b128 v[44:47], v241 offset:34816
	ds_read_b128 v[76:79], v42 offset:53248
	ds_read_b128 v[60:63], v242 offset:34816
	ds_read_b128 v[48:51], v241 offset:34848
	ds_read_b128 v[80:83], v42 offset:53280
	ds_read_b128 v[64:67], v242 offset:34848
	ds_read_b128 v[52:55], v241 offset:34880
	ds_read_b128 v[84:87], v42 offset:53312
	ds_read_b128 v[68:71], v242 offset:34880
	ds_read_b128 v[56:59], v241 offset:34912
	ds_read_b128 v[88:91], v42 offset:53344
	ds_read_b128 v[72:75], v242 offset:34912
	s_waitcnt lgkmcnt(10)
	v_mfma_f32_32x32x16_bf16 v[18:33], v[44:47], v[76:79], 0
	s_waitcnt lgkmcnt(9)
	v_mfma_f32_32x32x16_bf16 v[2:17], v[60:63], v[76:79], 0
	s_waitcnt lgkmcnt(7)
	v_mfma_f32_32x32x16_bf16 v[18:33], v[48:51], v[80:83], v[18:33]
	s_waitcnt lgkmcnt(6)
	v_mfma_f32_32x32x16_bf16 v[2:17], v[64:67], v[80:83], v[2:17]
	s_waitcnt lgkmcnt(4)
	v_mfma_f32_32x32x16_bf16 v[18:33], v[52:55], v[84:87], v[18:33]
	s_waitcnt lgkmcnt(3)
	v_mfma_f32_32x32x16_bf16 v[2:17], v[68:71], v[84:87], v[2:17]
	s_waitcnt lgkmcnt(1)
	v_mfma_f32_32x32x16_bf16 v[18:33], v[56:59], v[88:91], v[18:33]
	s_waitcnt lgkmcnt(0)
	v_mfma_f32_32x32x16_bf16 v[2:17], v[72:75], v[88:91], v[2:17]
	s_cbranch_vccnz .LBB0_307
	ds_read_b128 v[110:113], v243
	ds_read_b128 v[106:109], v243 offset:32
	ds_read_b128 v[102:105], v243 offset:64
	ds_read_b128 v[98:101], v243 offset:96
	ds_read_b128 v[94:97], v243 offset:128
	ds_read_b128 v[90:93], v243 offset:160
	ds_read_b128 v[86:89], v243 offset:192
	ds_read_b128 v[82:85], v243 offset:224
	v_add_u32_e32 v119, v171, v172
	ds_read_b128 v[66:69], v119
	ds_read_b128 v[114:117], v244 offset:17408
	v_readlane_b32 s64, v254, 53
	v_readlane_b32 s65, v254, 54
	s_andn2_b64 vcc, exec, s[64:65]
	s_mov_b64 s[64:65], -1
	s_cbranch_vccnz .LBB0_319
	s_waitcnt lgkmcnt(0)
	v_mfma_f32_32x32x16_bf16 v[50:65], v[114:117], v[110:113], 0
	ds_read_b128 v[34:37], v244 offset:17440
	ds_read_b128 v[70:73], v119 offset:224
	v_readlane_b32 s64, v254, 47
	v_readlane_b32 s65, v254, 48
	s_waitcnt lgkmcnt(0)
	v_mfma_f32_32x32x16_bf16 v[50:65], v[34:37], v[106:109], v[50:65]
	ds_read_b128 v[34:37], v244 offset:17472
	ds_read_b128 v[38:41], v244 offset:17504
	s_waitcnt lgkmcnt(0)
	v_mfma_f32_32x32x16_bf16 v[50:65], v[34:37], v[102:105], v[50:65]
	v_mfma_f32_32x32x16_bf16 v[50:65], v[38:41], v[98:101], v[50:65]
	ds_read_b128 v[34:37], v244 offset:17536
	ds_read_b128 v[38:41], v244 offset:17568
	s_waitcnt lgkmcnt(0)
	v_mfma_f32_32x32x16_bf16 v[50:65], v[34:37], v[94:97], v[50:65]
	v_mfma_f32_32x32x16_bf16 v[50:65], v[38:41], v[90:93], v[50:65]
	ds_read_b128 v[34:37], v244 offset:17600
	ds_read_b128 v[38:41], v244 offset:17632
	ds_read_b128 v[74:77], v119 offset:32
	ds_read_b128 v[78:81], v119 offset:64
	s_waitcnt lgkmcnt(0)
	v_mfma_f32_32x32x16_bf16 v[50:65], v[34:37], v[86:89], v[50:65]
	v_mfma_f32_32x32x16_bf16 v[50:65], v[38:41], v[82:85], v[50:65]
	v_mfma_f32_32x32x16_bf16 v[34:49], v[66:69], v[110:113], 0
	s_nop 10
	v_cndmask_b32_e64 v182, v50, 0, s[64:65]
	v_readlane_b32 s64, v254, 55
	v_readlane_b32 s65, v254, 56
	v_cndmask_b32_e64 v50, v182, v50, s[60:61]
	v_cndmask_b32_e64 v51, 0, v51, s[60:61]
	v_cndmask_b32_e64 v52, v52, 0, s[64:65]
	v_readlane_b32 s64, v254, 57
	v_mfma_f32_32x32x16_bf16 v[34:49], v[74:77], v[106:109], v[34:49]
	v_readlane_b32 s65, v254, 58
	v_cndmask_b32_e64 v59, v59, 0, s[76:77]
	v_cndmask_b32_e64 v60, v60, 0, s[78:79]
	v_cndmask_b32_e64 v53, v53, 0, s[64:65]
	v_readlane_b32 s64, v254, 59
	v_readlane_b32 s65, v254, 60
	v_cndmask_b32_e64 v61, v61, 0, s[80:81]
	v_mfma_f32_32x32x16_bf16 v[34:49], v[78:81], v[102:105], v[34:49]
	ds_read_b128 v[74:77], v119 offset:96
	ds_read_b128 v[78:81], v119 offset:128
	v_cndmask_b32_e64 v54, v54, 0, s[64:65]
	v_readlane_b32 s64, v254, 61
	v_readlane_b32 s65, v254, 62
	v_cndmask_b32_e64 v62, v62, 0, s[82:83]
	v_cndmask_b32_e64 v63, v63, 0, s[84:85]
	v_cndmask_b32_e64 v55, v55, 0, s[64:65]
	s_waitcnt lgkmcnt(0)
	v_mfma_f32_32x32x16_bf16 v[34:49], v[74:77], v[98:101], v[34:49]
	v_readlane_b32 s64, v254, 63
	v_readlane_b32 s65, v255, 0
	v_cndmask_b32_e64 v64, v64, 0, s[86:87]
	v_cndmask_b32_e64 v65, v65, 0, s[66:67]
	v_cndmask_b32_e64 v56, v56, 0, s[64:65]
	v_readlane_b32 s64, v255, 1
	v_readlane_b32 s65, v255, 2
	v_mfma_f32_32x32x16_bf16 v[34:49], v[78:81], v[94:97], v[34:49]
	ds_read_b128 v[74:77], v119 offset:160
	ds_read_b128 v[78:81], v119 offset:192
	v_cndmask_b32_e64 v57, v57, 0, s[64:65]
	v_readlane_b32 s64, v255, 3
	v_readlane_b32 s65, v255, 4
	s_nop 1
	v_cndmask_b32_e64 v58, v58, 0, s[64:65]
	s_waitcnt lgkmcnt(0)
	v_mfma_f32_32x32x16_bf16 v[34:49], v[74:77], v[90:93], v[34:49]
	s_mov_b64 s[64:65], 0
	v_mfma_f32_32x32x16_bf16 v[34:49], v[78:81], v[86:89], v[34:49]
	v_mfma_f32_32x32x16_bf16 v[34:49], v[70:73], v[82:85], v[34:49]
